# speedup vs baseline: 1.0102x; 1.0050x over previous
; __device__ __forceinline__ void store_inproj(float* st, KP p, int grow0, int bcol, int tix) {
;     ...
;   for (int it = tix; it < 128 * 32; it += NTHREADS) {
;     const int r = it >> 5, ch = it & 31;
;     const int gcol = bcol + ch * 8;
;     const int grp = gcol >> 9;
;     const int cin = gcol & 511;
;     int rbase;
;     switch (grp) {
;       case 0: rbase = 0; break; case 1: rbase = 512; break; case 3: rbase = 1024; break; case 4: rbase = 1536; break;
;       case 6: rbase = 2048; break; case 7: rbase = 2560; break; case 8: rbase = 3072; break; case 10: rbase = 3584; break;
;       default: rbase = -1; break;
;     }
;     if (rbase < 0) continue;
;     float* sp = st + r * STS + ch * 8;
;     u16* drow = Rb + (size_t)(grow0 + r) * RLD + rbase + cin;
;     const float posf = (float)(pos0 + r - PADF);
.LBB0_459:
	s_and_b64 vcc, exec, s[6:7]
	s_cbranch_vccz .LBB0_424
	s_cmp_lt_i32 s48, 2
	s_cbranch_scc1 .Lrm1_dq
	s_cmp_eq_u32 s48, 7
	s_cbranch_scc1 .Lrm1_rq
	s_cmp_eq_u32 s48, 8
	s_cbranch_scc1 .Lrm1_rq
	v_ashrrev_i32_e32 v68, 5, v89
	v_and_b32_e32 v183, 0xf8, v88
	s_branch .Lrm1_done
.Lrm1_rq:
	v_and_b32_e32 v68, 0x7ff, v89
	v_and_b32_e32 v183, 7, v68
	v_and_b32_e32 v0, 8, v68
	v_lshrrev_b32_e32 v68, 4, v68
	v_lshlrev_b32_e32 v183, 3, v183
	v_lshl_or_b32 v183, v0, 4, v183
	v_lshrrev_b32_e32 v0, 5, v89
	v_and_or_b32 v183, v0, 64, v183
	s_branch .Lrm1_done

; __device__ __forceinline__ void store_inproj(float* st, KP p, int grow0, int bcol, int tix) {
;     ...
;   for (int it = tix; it < 128 * 32; it += NTHREADS) {
;     const int r = it >> 5, ch = it & 31;
;     const int gcol = bcol + ch * 8;
;     const int grp = gcol >> 9;
;     const int cin = gcol & 511;
;     int rbase;
;     switch (grp) {
;       case 0: rbase = 0; break; case 1: rbase = 512; break; case 3: rbase = 1024; break; case 4: rbase = 1536; break;
;       case 6: rbase = 2048; break; case 7: rbase = 2560; break; case 8: rbase = 3072; break; case 10: rbase = 3584; break;
;       default: rbase = -1; break;
;     }
;     if (rbase < 0) continue;
;     float* sp = st + r * STS + ch * 8;
;     u16* drow = Rb + (size_t)(grow0 + r) * RLD + rbase + cin;
;     const float posf = (float)(pos0 + r - PADF);
.LBB0_536:
	s_and_b64 vcc, exec, s[6:7]
	s_cbranch_vccz .LBB0_501
	s_cmp_lt_i32 s48, 2
	s_cbranch_scc1 .Lrm2_dq
	s_cmp_eq_u32 s48, 7
	s_cbranch_scc1 .Lrm2_rq
	s_cmp_eq_u32 s48, 8
	s_cbranch_scc1 .Lrm2_rq
	v_ashrrev_i32_e32 v4, 5, v22
	v_and_b32_e32 v183, 0xf8, v86
	s_branch .Lrm2_done
.Lrm2_rq:
	v_and_b32_e32 v4, 0x7ff, v22
	v_and_b32_e32 v183, 7, v4
	v_and_b32_e32 v0, 8, v4
	v_lshrrev_b32_e32 v4, 4, v4
	v_lshlrev_b32_e32 v183, 3, v183
	v_lshl_or_b32 v183, v0, 4, v183
	v_lshrrev_b32_e32 v0, 5, v22
	v_and_or_b32 v183, v0, 64, v183
	s_branch .Lrm2_done
